# FF1 epilogue hand-scheduled in place + trailing-half restore barrier moved behind next-unit scheduling (G3)
# speedup vs baseline: 1.0004x; 1.0004x over previous
.LBB0_319:
	s_mov_b32 s72, s5
	s_ashr_i32 s73, s5, 31
	s_xor_b64 s[78:79], s[76:77], -1
	s_lshl_b64 s[2:3], s[72:73], 19
	s_add_u32 s80, s48, s2
	s_addc_u32 s81, s49, s3
	s_and_b64 s[2:3], s[76:77], exec
	s_cselect_b32 s5, s81, s9
	s_cselect_b32 s29, s80, s8
	s_cmp_gt_i32 s72, 63
	s_cselect_b64 s[82:83], -1, 0
	s_lshl_b32 s2, s72, 6
	v_mov_b32_e32 v132, v133
	s_addk_i32 s2, 0xf000
	v_ashrrev_i32_e32 v133, 31, v132
	s_ashr_i32 s3, s2, 31
	v_lshlrev_b64 v[134:135], 19, v[132:133]
	s_lshl_b64 s[2:3], s[2:3], 2
	v_lshl_add_u64 v[134:135], s[6:7], 0, v[134:135]
	s_add_u32 s84, s12, s2
	v_cndmask_b32_e64 v133, v131, v135, s[76:77]
	v_cndmask_b32_e64 v138, v130, v134, s[76:77]
	s_addc_u32 s85, s88, s3
	s_mov_b32 s34, 0
	s_cmp_eq_u32 s41, 0
	s_cbranch_scc1 .Ltb_g3_skip
	s_andn2_b64 vcc, exec, s[50:51]
	s_cbranch_vccnz .Ltb_g3_skip
	s_barrier
.Ltb_g3_skip:
.LBB0_320:
	s_cmp_eq_u32 s34, 14
	s_cselect_b64 s[2:3], -1, 0
	s_and_b64 s[86:87], s[76:77], s[2:3]
	s_and_b64 s[86:87], s[86:87], s[0:1]
	s_and_b64 s[86:87], s[86:87], s[82:83]
	s_andn2_b64 vcc, exec, s[86:87]
	s_cbranch_vccnz .LBB0_332
	s_and_b64 vcc, exec, s[38:39]
	s_cbranch_vccnz .LBB0_331
	s_mov_b32 s16, 0x400001
	s_branch .LBB0_324

.LBB0_340:
	s_movk_i32 s16, 0x1600
	s_mov_b32 s5, s17
	v_mul_u32_u24_e32 v144, 0x1600, v136
	v_lshl_add_u32 v144, v192, 8, v144
	v_add3_u32 v144, v144, s4, v0
	v_mul_f32_e32 v133, 0xbfb8aa3b, v142
	v_mul_f32_e32 v137, v142, v142
	v_mul_f32_e32 v94, v126, v94
	v_mul_f32_e32 v95, v127, v95
	v_mul_f32_e32 v96, v128, v96
	v_mul_f32_e32 v97, v129, v97
	v_mul_f32_e32 v90, v122, v90
	v_mul_f32_e32 v91, v123, v91
	v_mul_f32_e32 v92, v124, v92
	v_mul_f32_e32 v93, v125, v93
	v_mul_f32_e32 v126, v133, v126
	v_mul_f32_e32 v127, v133, v127
	v_mul_f32_e32 v128, v133, v128
	v_mul_f32_e32 v129, v133, v129
	v_mul_f32_e32 v122, v133, v122
	v_mul_f32_e32 v123, v133, v123
	v_mul_f32_e32 v124, v133, v124
	v_mul_f32_e32 v125, v133, v125
	v_exp_f32_e32 v126, v126
	v_exp_f32_e32 v127, v127
	v_exp_f32_e32 v128, v128
	v_exp_f32_e32 v129, v129
	v_exp_f32_e32 v122, v122
	v_exp_f32_e32 v123, v123
	v_exp_f32_e32 v124, v124
	v_exp_f32_e32 v125, v125
	v_mul_f32_e32 v94, v137, v94
	v_mul_f32_e32 v95, v137, v95
	v_mul_f32_e32 v96, v137, v96
	v_mul_f32_e32 v97, v137, v97
	v_mul_f32_e32 v90, v137, v90
	v_mul_f32_e32 v91, v137, v91
	v_mul_f32_e32 v92, v137, v92
	v_mul_f32_e32 v93, v137, v93
	v_add_f32_e32 v126, 1.0, v126
	v_add_f32_e32 v127, 1.0, v127
	v_add_f32_e32 v128, 1.0, v128
	v_add_f32_e32 v129, 1.0, v129
	v_add_f32_e32 v122, 1.0, v122
	v_add_f32_e32 v123, 1.0, v123
	v_add_f32_e32 v124, 1.0, v124
	v_add_f32_e32 v125, 1.0, v125
	v_rcp_f32_e32 v126, v126
	v_rcp_f32_e32 v127, v127
	v_rcp_f32_e32 v128, v128
	v_rcp_f32_e32 v129, v129
	v_rcp_f32_e32 v122, v122
	v_rcp_f32_e32 v123, v123
	v_rcp_f32_e32 v124, v124
	v_rcp_f32_e32 v125, v125
	v_mul_f32_e32 v94, v126, v94
	v_mul_f32_e32 v95, v127, v95
	v_mul_f32_e32 v96, v128, v96
	v_mul_f32_e32 v97, v129, v97
	v_mul_f32_e32 v90, v122, v90
	v_mul_f32_e32 v91, v123, v91
	v_mul_f32_e32 v92, v124, v92
	v_mul_f32_e32 v93, v125, v93
	v_cvt_pk_bf16_f32 v94, v94, v95
	v_cvt_pk_bf16_f32 v95, v96, v97
	v_cvt_pk_bf16_f32 v96, v90, v91
	v_cvt_pk_bf16_f32 v97, v92, v93
	global_store_dwordx4 v144, v[94:97], s[52:53]
	v_mul_f32_e32 v145, 0xbfb8aa3b, v158
	v_mul_f32_e32 v161, v158, v158
	v_mul_f32_e32 v86, v118, v86
	v_mul_f32_e32 v87, v119, v87
	v_mul_f32_e32 v88, v120, v88
	v_mul_f32_e32 v89, v121, v89
	v_mul_f32_e32 v82, v114, v82
	v_mul_f32_e32 v83, v115, v83
	v_mul_f32_e32 v84, v116, v84
	v_mul_f32_e32 v85, v117, v85
	v_mul_f32_e32 v118, v145, v118
	v_mul_f32_e32 v119, v145, v119
	v_mul_f32_e32 v120, v145, v120
	v_mul_f32_e32 v121, v145, v121
	v_mul_f32_e32 v114, v145, v114
	v_mul_f32_e32 v115, v145, v115
	v_mul_f32_e32 v116, v145, v116
	v_mul_f32_e32 v117, v145, v117
	v_exp_f32_e32 v118, v118
	v_exp_f32_e32 v119, v119
	v_exp_f32_e32 v120, v120
	v_exp_f32_e32 v121, v121
	v_exp_f32_e32 v114, v114
	v_exp_f32_e32 v115, v115
	v_exp_f32_e32 v116, v116
	v_exp_f32_e32 v117, v117
	v_mul_f32_e32 v86, v161, v86
	v_mul_f32_e32 v87, v161, v87
	v_mul_f32_e32 v88, v161, v88
	v_mul_f32_e32 v89, v161, v89
	v_mul_f32_e32 v82, v161, v82
	v_mul_f32_e32 v83, v161, v83
	v_mul_f32_e32 v84, v161, v84
	v_mul_f32_e32 v85, v161, v85
	v_add_f32_e32 v118, 1.0, v118
	v_add_f32_e32 v119, 1.0, v119
	v_add_f32_e32 v120, 1.0, v120
	v_add_f32_e32 v121, 1.0, v121
	v_add_f32_e32 v114, 1.0, v114
	v_add_f32_e32 v115, 1.0, v115
	v_add_f32_e32 v116, 1.0, v116
	v_add_f32_e32 v117, 1.0, v117
	v_rcp_f32_e32 v118, v118
	v_rcp_f32_e32 v119, v119
	v_rcp_f32_e32 v120, v120
	v_rcp_f32_e32 v121, v121
	v_rcp_f32_e32 v114, v114
	v_rcp_f32_e32 v115, v115
	v_rcp_f32_e32 v116, v116
	v_rcp_f32_e32 v117, v117
	v_mul_f32_e32 v86, v118, v86
	v_mul_f32_e32 v87, v119, v87
	v_mul_f32_e32 v88, v120, v88
	v_mul_f32_e32 v89, v121, v89
	v_mul_f32_e32 v82, v114, v82
	v_mul_f32_e32 v83, v115, v83
	v_mul_f32_e32 v84, v116, v84
	v_mul_f32_e32 v85, v117, v85
	v_cvt_pk_bf16_f32 v86, v86, v87
	v_cvt_pk_bf16_f32 v87, v88, v89
	v_cvt_pk_bf16_f32 v88, v82, v83
	v_cvt_pk_bf16_f32 v89, v84, v85
	v_add_u32_e32 v160, 0x16000, v144
	global_store_dwordx4 v160, v[86:89], s[52:53]
	v_mul_f32_e32 v133, 0xbfb8aa3b, v156
	v_mul_f32_e32 v137, v156, v156
	v_mul_f32_e32 v78, v110, v78
	v_mul_f32_e32 v79, v111, v79
	v_mul_f32_e32 v80, v112, v80
	v_mul_f32_e32 v81, v113, v81
	v_mul_f32_e32 v74, v106, v74
	v_mul_f32_e32 v75, v107, v75
	v_mul_f32_e32 v76, v108, v76
	v_mul_f32_e32 v77, v109, v77
	v_mul_f32_e32 v110, v133, v110
	v_mul_f32_e32 v111, v133, v111
	v_mul_f32_e32 v112, v133, v112
	v_mul_f32_e32 v113, v133, v113
	v_mul_f32_e32 v106, v133, v106
	v_mul_f32_e32 v107, v133, v107
	v_mul_f32_e32 v108, v133, v108
	v_mul_f32_e32 v109, v133, v109
	v_exp_f32_e32 v110, v110
	v_exp_f32_e32 v111, v111
	v_exp_f32_e32 v112, v112
	v_exp_f32_e32 v113, v113
	v_exp_f32_e32 v106, v106
	v_exp_f32_e32 v107, v107
	v_exp_f32_e32 v108, v108
	v_exp_f32_e32 v109, v109
	v_mul_f32_e32 v78, v137, v78
	v_mul_f32_e32 v79, v137, v79
	v_mul_f32_e32 v80, v137, v80
	v_mul_f32_e32 v81, v137, v81
	v_mul_f32_e32 v74, v137, v74
	v_mul_f32_e32 v75, v137, v75
	v_mul_f32_e32 v76, v137, v76
	v_mul_f32_e32 v77, v137, v77
	v_add_f32_e32 v110, 1.0, v110
	v_add_f32_e32 v111, 1.0, v111
	v_add_f32_e32 v112, 1.0, v112
	v_add_f32_e32 v113, 1.0, v113
	v_add_f32_e32 v106, 1.0, v106
	v_add_f32_e32 v107, 1.0, v107
	v_add_f32_e32 v108, 1.0, v108
	v_add_f32_e32 v109, 1.0, v109
	v_rcp_f32_e32 v110, v110
	v_rcp_f32_e32 v111, v111
	v_rcp_f32_e32 v112, v112
	v_rcp_f32_e32 v113, v113
	v_rcp_f32_e32 v106, v106
	v_rcp_f32_e32 v107, v107
	v_rcp_f32_e32 v108, v108
	v_rcp_f32_e32 v109, v109
	v_mul_f32_e32 v78, v110, v78
	v_mul_f32_e32 v79, v111, v79
	v_mul_f32_e32 v80, v112, v80
	v_mul_f32_e32 v81, v113, v81
	v_mul_f32_e32 v74, v106, v74
	v_mul_f32_e32 v75, v107, v75
	v_mul_f32_e32 v76, v108, v76
	v_mul_f32_e32 v77, v109, v77
	v_cvt_pk_bf16_f32 v78, v78, v79
	v_cvt_pk_bf16_f32 v79, v80, v81
	v_cvt_pk_bf16_f32 v80, v74, v75
	v_cvt_pk_bf16_f32 v81, v76, v77
	v_add_u32_e32 v160, 0x2c000, v144
	global_store_dwordx4 v160, v[78:81], s[52:53]
	v_mul_f32_e32 v145, 0xbfb8aa3b, v154
	v_mul_f32_e32 v161, v154, v154
	v_mul_f32_e32 v70, v102, v70
	v_mul_f32_e32 v71, v103, v71
	v_mul_f32_e32 v72, v104, v72
	v_mul_f32_e32 v73, v105, v73
	v_mul_f32_e32 v66, v98, v66
	v_mul_f32_e32 v67, v99, v67
	v_mul_f32_e32 v68, v100, v68
	v_mul_f32_e32 v69, v101, v69
	v_mul_f32_e32 v102, v145, v102
	v_mul_f32_e32 v103, v145, v103
	v_mul_f32_e32 v104, v145, v104
	v_mul_f32_e32 v105, v145, v105
	v_mul_f32_e32 v98, v145, v98
	v_mul_f32_e32 v99, v145, v99
	v_mul_f32_e32 v100, v145, v100
	v_mul_f32_e32 v101, v145, v101
	v_exp_f32_e32 v102, v102
	v_exp_f32_e32 v103, v103
	v_exp_f32_e32 v104, v104
	v_exp_f32_e32 v105, v105
	v_exp_f32_e32 v98, v98
	v_exp_f32_e32 v99, v99
	v_exp_f32_e32 v100, v100
	v_exp_f32_e32 v101, v101
	v_mul_f32_e32 v70, v161, v70
	v_mul_f32_e32 v71, v161, v71
	v_mul_f32_e32 v72, v161, v72
	v_mul_f32_e32 v73, v161, v73
	v_mul_f32_e32 v66, v161, v66
	v_mul_f32_e32 v67, v161, v67
	v_mul_f32_e32 v68, v161, v68
	v_mul_f32_e32 v69, v161, v69
	v_add_f32_e32 v102, 1.0, v102
	v_add_f32_e32 v103, 1.0, v103
	v_add_f32_e32 v104, 1.0, v104
	v_add_f32_e32 v105, 1.0, v105
	v_add_f32_e32 v98, 1.0, v98
	v_add_f32_e32 v99, 1.0, v99
	v_add_f32_e32 v100, 1.0, v100
	v_add_f32_e32 v101, 1.0, v101
	v_rcp_f32_e32 v102, v102
	v_rcp_f32_e32 v103, v103
	v_rcp_f32_e32 v104, v104
	v_rcp_f32_e32 v105, v105
	v_rcp_f32_e32 v98, v98
	v_rcp_f32_e32 v99, v99
	v_rcp_f32_e32 v100, v100
	v_rcp_f32_e32 v101, v101
	v_mul_f32_e32 v70, v102, v70
	v_mul_f32_e32 v71, v103, v71
	v_mul_f32_e32 v72, v104, v72
	v_mul_f32_e32 v73, v105, v73
	v_mul_f32_e32 v66, v98, v66
	v_mul_f32_e32 v67, v99, v67
	v_mul_f32_e32 v68, v100, v68
	v_mul_f32_e32 v69, v101, v69
	v_cvt_pk_bf16_f32 v70, v70, v71
	v_cvt_pk_bf16_f32 v71, v72, v73
	v_cvt_pk_bf16_f32 v72, v66, v67
	v_cvt_pk_bf16_f32 v73, v68, v69
	v_add_u32_e32 v160, 0x42000, v144
	global_store_dwordx4 v160, v[70:73], s[52:53]
	v_mul_f32_e32 v133, 0xbfb8aa3b, v152
	v_mul_f32_e32 v137, v152, v152
	v_mul_f32_e32 v30, v62, v30
	v_mul_f32_e32 v31, v63, v31
	v_mul_f32_e32 v32, v64, v32
	v_mul_f32_e32 v33, v65, v33
	v_mul_f32_e32 v26, v58, v26
	v_mul_f32_e32 v27, v59, v27
	v_mul_f32_e32 v28, v60, v28
	v_mul_f32_e32 v29, v61, v29
	v_mul_f32_e32 v62, v133, v62
	v_mul_f32_e32 v63, v133, v63
	v_mul_f32_e32 v64, v133, v64
	v_mul_f32_e32 v65, v133, v65
	v_mul_f32_e32 v58, v133, v58
	v_mul_f32_e32 v59, v133, v59
	v_mul_f32_e32 v60, v133, v60
	v_mul_f32_e32 v61, v133, v61
	v_exp_f32_e32 v62, v62
	v_exp_f32_e32 v63, v63
	v_exp_f32_e32 v64, v64
	v_exp_f32_e32 v65, v65
	v_exp_f32_e32 v58, v58
	v_exp_f32_e32 v59, v59
	v_exp_f32_e32 v60, v60
	v_exp_f32_e32 v61, v61
	v_mul_f32_e32 v30, v137, v30
	v_mul_f32_e32 v31, v137, v31
	v_mul_f32_e32 v32, v137, v32
	v_mul_f32_e32 v33, v137, v33
	v_mul_f32_e32 v26, v137, v26
	v_mul_f32_e32 v27, v137, v27
	v_mul_f32_e32 v28, v137, v28
	v_mul_f32_e32 v29, v137, v29
	v_add_f32_e32 v62, 1.0, v62
	v_add_f32_e32 v63, 1.0, v63
	v_add_f32_e32 v64, 1.0, v64
	v_add_f32_e32 v65, 1.0, v65
	v_add_f32_e32 v58, 1.0, v58
	v_add_f32_e32 v59, 1.0, v59
	v_add_f32_e32 v60, 1.0, v60
	v_add_f32_e32 v61, 1.0, v61
	v_rcp_f32_e32 v62, v62
	v_rcp_f32_e32 v63, v63
	v_rcp_f32_e32 v64, v64
	v_rcp_f32_e32 v65, v65
	v_rcp_f32_e32 v58, v58
	v_rcp_f32_e32 v59, v59
	v_rcp_f32_e32 v60, v60
	v_rcp_f32_e32 v61, v61
	v_mul_f32_e32 v30, v62, v30
	v_mul_f32_e32 v31, v63, v31
	v_mul_f32_e32 v32, v64, v32
	v_mul_f32_e32 v33, v65, v33
	v_mul_f32_e32 v26, v58, v26
	v_mul_f32_e32 v27, v59, v27
	v_mul_f32_e32 v28, v60, v28
	v_mul_f32_e32 v29, v61, v29
	v_cvt_pk_bf16_f32 v30, v30, v31
	v_cvt_pk_bf16_f32 v31, v32, v33
	v_cvt_pk_bf16_f32 v32, v26, v27
	v_cvt_pk_bf16_f32 v33, v28, v29
	v_add_u32_e32 v160, 0xb0000, v144
	global_store_dwordx4 v160, v[30:33], s[52:53]
	v_mul_f32_e32 v145, 0xbfb8aa3b, v150
	v_mul_f32_e32 v161, v150, v150
	v_mul_f32_e32 v22, v54, v22
	v_mul_f32_e32 v23, v55, v23
	v_mul_f32_e32 v24, v56, v24
	v_mul_f32_e32 v25, v57, v25
	v_mul_f32_e32 v18, v50, v18
	v_mul_f32_e32 v19, v51, v19
	v_mul_f32_e32 v20, v52, v20
	v_mul_f32_e32 v21, v53, v21
	v_mul_f32_e32 v54, v145, v54
	v_mul_f32_e32 v55, v145, v55
	v_mul_f32_e32 v56, v145, v56
	v_mul_f32_e32 v57, v145, v57
	v_mul_f32_e32 v50, v145, v50
	v_mul_f32_e32 v51, v145, v51
	v_mul_f32_e32 v52, v145, v52
	v_mul_f32_e32 v53, v145, v53
	v_exp_f32_e32 v54, v54
	v_exp_f32_e32 v55, v55
	v_exp_f32_e32 v56, v56
	v_exp_f32_e32 v57, v57
	v_exp_f32_e32 v50, v50
	v_exp_f32_e32 v51, v51
	v_exp_f32_e32 v52, v52
	v_exp_f32_e32 v53, v53
	v_mul_f32_e32 v22, v161, v22
	v_mul_f32_e32 v23, v161, v23
	v_mul_f32_e32 v24, v161, v24
	v_mul_f32_e32 v25, v161, v25
	v_mul_f32_e32 v18, v161, v18
	v_mul_f32_e32 v19, v161, v19
	v_mul_f32_e32 v20, v161, v20
	v_mul_f32_e32 v21, v161, v21
	v_add_f32_e32 v54, 1.0, v54
	v_add_f32_e32 v55, 1.0, v55
	v_add_f32_e32 v56, 1.0, v56
	v_add_f32_e32 v57, 1.0, v57
	v_add_f32_e32 v50, 1.0, v50
	v_add_f32_e32 v51, 1.0, v51
	v_add_f32_e32 v52, 1.0, v52
	v_add_f32_e32 v53, 1.0, v53
	v_rcp_f32_e32 v54, v54
	v_rcp_f32_e32 v55, v55
	v_rcp_f32_e32 v56, v56
	v_rcp_f32_e32 v57, v57
	v_rcp_f32_e32 v50, v50
	v_rcp_f32_e32 v51, v51
	v_rcp_f32_e32 v52, v52
	v_rcp_f32_e32 v53, v53
	v_mul_f32_e32 v22, v54, v22
	v_mul_f32_e32 v23, v55, v23
	v_mul_f32_e32 v24, v56, v24
	v_mul_f32_e32 v25, v57, v25
	v_mul_f32_e32 v18, v50, v18
	v_mul_f32_e32 v19, v51, v19
	v_mul_f32_e32 v20, v52, v20
	v_mul_f32_e32 v21, v53, v21
	v_cvt_pk_bf16_f32 v22, v22, v23
	v_cvt_pk_bf16_f32 v23, v24, v25
	v_cvt_pk_bf16_f32 v24, v18, v19
	v_cvt_pk_bf16_f32 v25, v20, v21
	v_add_u32_e32 v160, 0xc6000, v144
	global_store_dwordx4 v160, v[22:25], s[52:53]
	v_mul_f32_e32 v133, 0xbfb8aa3b, v140
	v_mul_f32_e32 v137, v140, v140
	v_mul_f32_e32 v14, v46, v14
	v_mul_f32_e32 v15, v47, v15
	v_mul_f32_e32 v16, v48, v16
	v_mul_f32_e32 v17, v49, v17
	v_mul_f32_e32 v10, v42, v10
	v_mul_f32_e32 v11, v43, v11
	v_mul_f32_e32 v12, v44, v12
	v_mul_f32_e32 v13, v45, v13
	v_mul_f32_e32 v46, v133, v46
	v_mul_f32_e32 v47, v133, v47
	v_mul_f32_e32 v48, v133, v48
	v_mul_f32_e32 v49, v133, v49
	v_mul_f32_e32 v42, v133, v42
	v_mul_f32_e32 v43, v133, v43
	v_mul_f32_e32 v44, v133, v44
	v_mul_f32_e32 v45, v133, v45
	v_exp_f32_e32 v46, v46
	v_exp_f32_e32 v47, v47
	v_exp_f32_e32 v48, v48
	v_exp_f32_e32 v49, v49
	v_exp_f32_e32 v42, v42
	v_exp_f32_e32 v43, v43
	v_exp_f32_e32 v44, v44
	v_exp_f32_e32 v45, v45
	v_mul_f32_e32 v14, v137, v14
	v_mul_f32_e32 v15, v137, v15
	v_mul_f32_e32 v16, v137, v16
	v_mul_f32_e32 v17, v137, v17
	v_mul_f32_e32 v10, v137, v10
	v_mul_f32_e32 v11, v137, v11
	v_mul_f32_e32 v12, v137, v12
	v_mul_f32_e32 v13, v137, v13
	v_add_f32_e32 v46, 1.0, v46
	v_add_f32_e32 v47, 1.0, v47
	v_add_f32_e32 v48, 1.0, v48
	v_add_f32_e32 v49, 1.0, v49
	v_add_f32_e32 v42, 1.0, v42
	v_add_f32_e32 v43, 1.0, v43
	v_add_f32_e32 v44, 1.0, v44
	v_add_f32_e32 v45, 1.0, v45
	v_rcp_f32_e32 v46, v46
	v_rcp_f32_e32 v47, v47
	v_rcp_f32_e32 v48, v48
	v_rcp_f32_e32 v49, v49
	v_rcp_f32_e32 v42, v42
	v_rcp_f32_e32 v43, v43
	v_rcp_f32_e32 v44, v44
	v_rcp_f32_e32 v45, v45
	v_mul_f32_e32 v14, v46, v14
	v_mul_f32_e32 v15, v47, v15
	v_mul_f32_e32 v16, v48, v16
	v_mul_f32_e32 v17, v49, v17
	v_mul_f32_e32 v10, v42, v10
	v_mul_f32_e32 v11, v43, v11
	v_mul_f32_e32 v12, v44, v12
	v_mul_f32_e32 v13, v45, v13
	v_cvt_pk_bf16_f32 v14, v14, v15
	v_cvt_pk_bf16_f32 v15, v16, v17
	v_cvt_pk_bf16_f32 v16, v10, v11
	v_cvt_pk_bf16_f32 v17, v12, v13
	v_add_u32_e32 v160, 0xdc000, v144
	global_store_dwordx4 v160, v[14:17], s[52:53]
	v_mul_f32_e32 v145, 0xbfb8aa3b, v138
	v_mul_f32_e32 v161, v138, v138
	v_mul_f32_e32 v6, v38, v6
	v_mul_f32_e32 v7, v39, v7
	v_mul_f32_e32 v8, v40, v8
	v_mul_f32_e32 v9, v41, v9
	v_mul_f32_e32 v2, v34, v2
	v_mul_f32_e32 v3, v35, v3
	v_mul_f32_e32 v4, v36, v4
	v_mul_f32_e32 v5, v37, v5
	v_mul_f32_e32 v38, v145, v38
	v_mul_f32_e32 v39, v145, v39
	v_mul_f32_e32 v40, v145, v40
	v_mul_f32_e32 v41, v145, v41
	v_mul_f32_e32 v34, v145, v34
	v_mul_f32_e32 v35, v145, v35
	v_mul_f32_e32 v36, v145, v36
	v_mul_f32_e32 v37, v145, v37
	v_exp_f32_e32 v38, v38
	v_exp_f32_e32 v39, v39
	v_exp_f32_e32 v40, v40
	v_exp_f32_e32 v41, v41
	v_exp_f32_e32 v34, v34
	v_exp_f32_e32 v35, v35
	v_exp_f32_e32 v36, v36
	v_exp_f32_e32 v37, v37
	v_mul_f32_e32 v6, v161, v6
	v_mul_f32_e32 v7, v161, v7
	v_mul_f32_e32 v8, v161, v8
	v_mul_f32_e32 v9, v161, v9
	v_mul_f32_e32 v2, v161, v2
	v_mul_f32_e32 v3, v161, v3
	v_mul_f32_e32 v4, v161, v4
	v_mul_f32_e32 v5, v161, v5
	v_add_f32_e32 v38, 1.0, v38
	v_add_f32_e32 v39, 1.0, v39
	v_add_f32_e32 v40, 1.0, v40
	v_add_f32_e32 v41, 1.0, v41
	v_add_f32_e32 v34, 1.0, v34
	v_add_f32_e32 v35, 1.0, v35
	v_add_f32_e32 v36, 1.0, v36
	v_add_f32_e32 v37, 1.0, v37
	v_rcp_f32_e32 v38, v38
	v_rcp_f32_e32 v39, v39
	v_rcp_f32_e32 v40, v40
	v_rcp_f32_e32 v41, v41
	v_rcp_f32_e32 v34, v34
	v_rcp_f32_e32 v35, v35
	v_rcp_f32_e32 v36, v36
	v_rcp_f32_e32 v37, v37
	v_mul_f32_e32 v6, v38, v6
	v_mul_f32_e32 v7, v39, v7
	v_mul_f32_e32 v8, v40, v8
	v_mul_f32_e32 v9, v41, v9
	v_mul_f32_e32 v2, v34, v2
	v_mul_f32_e32 v3, v35, v3
	v_mul_f32_e32 v4, v36, v4
	v_mul_f32_e32 v5, v37, v5
	v_cvt_pk_bf16_f32 v6, v6, v7
	v_cvt_pk_bf16_f32 v7, v8, v9
	v_cvt_pk_bf16_f32 v8, v2, v3
	v_cvt_pk_bf16_f32 v9, v4, v5
	v_add_u32_e32 v160, 0xf2000, v144
	global_store_dwordx4 v160, v[6:9], s[52:53]
	s_and_b64 s[2:3], s[0:1], s[2:3]
	s_andn2_b64 vcc, exec, s[2:3]
	s_cbranch_vccnz .LBB0_348
	s_waitcnt vmcnt(0)
	s_and_saveexec_b64 s[2:3], s[44:45]
	s_cbranch_execz .LBB0_347
	s_mov_b64 s[84:85], exec
	v_mbcnt_lo_u32_b32 v133, s84, 0
	v_mbcnt_hi_u32_b32 v133, s85, v133
	v_cmp_eq_u32_e32 vcc, 0, v133
	s_and_saveexec_b64 s[82:83], vcc
	s_cbranch_execz .LBB0_344
	s_bcnt1_i32_b64 s5, s[84:85]
	v_mov_b32_e32 v136, s5
	s_waitcnt vmcnt(0)
	ds_add_rtn_u32 v136, v207, v136

.LBB0_349:
	s_andn2_b64 vcc, exec, s[50:51]
	s_cbranch_vccnz .LBB0_244
	s_branch .LBB0_244
